# pass 1: LF/VH row loads via SGPR base + 32-bit running offset + offset:imm (72 address instructions per unit removed); K loops without s_setprio
# baseline (speedup 1.0000x reference)
; #define LAS __attribute__((address_space(3)))
; __device__ __forceinline__ void hgrn_pass1_unit(Frame& F, int unit) {
;     ...
;     float lf[16], g[16]; unsigned short qv[16], vv[16];
; #pragma unroll
;     for (int i = 0; i < 16; ++i) { const size_t r = row0 + 16 * tq + i; lf[i] = LF[r * 512 + h * 128 + k]; qv[i] = QO[r * DM + h * 128 + k]; vv[i] = VH[r * 512 + h * 128 + k]; }
;     float run = 0.f;
; #pragma unroll
;     for (int i = 0; i < 16; ++i) { run += lf[i]; g[i] = run; }
;     tot[tq * 128 + k] = run;
;     { v4u w0, w1; w0.x = vv[0] | (vv[1] << 16); w0.y = vv[2] | (vv[3] << 16); w0.z = vv[4] | (vv[5] << 16); w0.w = vv[6] | (vv[7] << 16); w1.x = vv[8] | (vv[9] << 16); w1.y = vv[10] | (vv[11] << 16); w1.z = vv[12] | (vv[13] << 16); w1.w = vv[14] | (vv[15] << 16);
;       *(LAS v4u*)(VT + k * HG_LDS + 16 * tq) = w0; *(LAS v4u*)(VT + k * HG_LDS + 16 * tq + 8) = w1; }
;     __syncthreads();
.LBB0_526:
	s_ashr_i32 s82, s44, 9
	s_ashr_i32 s83, s82, 31
	s_lshl_b32 s2, s44, 6
	s_lshl_b64 s[82:83], s[82:83], 13
	s_and_b32 s2, s2, 0x1fc0
	s_or_b32 s82, s82, s2
	v_lshl_add_u64 v[0:1], s[82:83], 0, v[16:17]
	v_lshlrev_b64 v[2:3], 9, v[0:1]
	s_and_b32 s84, s44, 0x180
	v_or_b32_e32 v2, v2, v12
	v_or_b32_e32 v2, s84, v2
	v_lshlrev_b32_e32 v250, 2, v2
	v_lshlrev_b32_e32 v251, 1, v2
	s_lshl_b32 s68, s84, 1
	v_lshl_add_u64 v[72:73], v[18:19], 0, s[68:69]
	global_load_dword v95, v250, s[60:61]
	global_load_ushort v74, v251, s[64:65]
	v_lshlrev_b64 v[4:5], 11, v[0:1]
	v_or_b32_e32 v2, 1, v0
	v_mov_b32_e32 v3, v1
	v_lshl_add_u64 v[70:71], v[72:73], 0, v[4:5]
	v_lshlrev_b64 v[2:3], 11, v[2:3]
	v_lshl_add_u64 v[66:67], v[72:73], 0, v[2:3]
	global_load_dword v93, v250, s[60:61] offset:2048
	v_add_u32_e32 v250, 0x1000, v250
	global_load_ushort v75, v251, s[64:65] offset:1024
	v_or_b32_e32 v2, 2, v0
	v_mov_b32_e32 v3, v1
	v_lshlrev_b64 v[2:3], 11, v[2:3]
	v_lshl_add_u64 v[68:69], v[72:73], 0, v[2:3]
	global_load_dword v92, v250, s[60:61]
	global_load_ushort v76, v251, s[64:65] offset:2048
	v_or_b32_e32 v2, 3, v0
	v_mov_b32_e32 v3, v1
	v_lshlrev_b64 v[2:3], 11, v[2:3]
	v_lshl_add_u64 v[62:63], v[72:73], 0, v[2:3]
	global_load_dword v91, v250, s[60:61] offset:2048
	v_add_u32_e32 v250, 0x1000, v250
	global_load_ushort v77, v251, s[64:65] offset:3072
	v_add_u32_e32 v251, 0x1000, v251
	v_or_b32_e32 v2, 4, v0
	v_mov_b32_e32 v3, v1
	v_lshlrev_b64 v[2:3], 11, v[2:3]
	v_lshl_add_u64 v[64:65], v[72:73], 0, v[2:3]
	global_load_dword v89, v250, s[60:61]
	global_load_ushort v101, v251, s[64:65]
	v_or_b32_e32 v2, 5, v0
	v_mov_b32_e32 v3, v1
	v_lshlrev_b64 v[2:3], 11, v[2:3]
	v_lshl_add_u64 v[58:59], v[72:73], 0, v[2:3]
	global_load_dword v88, v250, s[60:61] offset:2048
	v_add_u32_e32 v250, 0x1000, v250
	global_load_ushort v104, v251, s[64:65] offset:1024
	v_or_b32_e32 v2, 6, v0
	v_mov_b32_e32 v3, v1
	v_lshlrev_b64 v[2:3], 11, v[2:3]
	v_lshl_add_u64 v[60:61], v[72:73], 0, v[2:3]
	global_load_dword v86, v250, s[60:61]
	global_load_ushort v107, v251, s[64:65] offset:2048
	v_or_b32_e32 v2, 7, v0
	v_mov_b32_e32 v3, v1
	v_lshlrev_b64 v[2:3], 11, v[2:3]
	v_lshl_add_u64 v[54:55], v[72:73], 0, v[2:3]
	global_load_dword v85, v250, s[60:61] offset:2048
	v_add_u32_e32 v250, 0x1000, v250
	global_load_ushort v108, v251, s[64:65] offset:3072
	v_add_u32_e32 v251, 0x1000, v251
	v_or_b32_e32 v2, 8, v0
	v_mov_b32_e32 v3, v1
	v_lshlrev_b64 v[2:3], 11, v[2:3]
	v_lshl_add_u64 v[56:57], v[72:73], 0, v[2:3]
	global_load_dword v83, v250, s[60:61]
	global_load_ushort v110, v251, s[64:65]
	v_or_b32_e32 v2, 9, v0
	v_mov_b32_e32 v3, v1
	v_lshlrev_b64 v[2:3], 11, v[2:3]
	v_lshl_add_u64 v[50:51], v[72:73], 0, v[2:3]
	global_load_dword v47, v250, s[60:61] offset:2048
	v_add_u32_e32 v250, 0x1000, v250
	global_load_ushort v112, v251, s[64:65] offset:1024
	v_or_b32_e32 v2, 10, v0
	v_mov_b32_e32 v3, v1
	v_lshlrev_b64 v[2:3], 11, v[2:3]
	v_lshl_add_u64 v[52:53], v[72:73], 0, v[2:3]
	global_load_dword v45, v250, s[60:61]
	global_load_ushort v115, v251, s[64:65] offset:2048
	v_or_b32_e32 v2, 11, v0
	v_mov_b32_e32 v3, v1
	v_lshlrev_b64 v[2:3], 11, v[2:3]
	global_load_dword v41, v250, s[60:61] offset:2048
	v_add_u32_e32 v250, 0x1000, v250
	v_lshl_add_u64 v[6:7], v[72:73], 0, v[2:3]
	global_load_ushort v117, v251, s[64:65] offset:3072
	v_add_u32_e32 v251, 0x1000, v251
	v_or_b32_e32 v2, 12, v0
	v_mov_b32_e32 v3, v1
	v_lshlrev_b64 v[2:3], 11, v[2:3]
	global_load_dword v39, v250, s[60:61]
	v_lshl_add_u64 v[48:49], v[72:73], 0, v[2:3]
	global_load_ushort v120, v251, s[64:65]
	v_or_b32_e32 v2, 13, v0
	v_mov_b32_e32 v3, v1
	global_load_dword v37, v250, s[60:61] offset:2048
	v_add_u32_e32 v250, 0x1000, v250
	global_load_ushort v126, v251, s[64:65] offset:1024
	v_or_b32_e32 v4, 14, v0
	v_mov_b32_e32 v5, v1
	v_or_b32_e32 v0, 15, v0
	global_load_ushort v127, v251, s[64:65] offset:2048
	v_lshlrev_b64 v[96:97], 9, v[0:1]
	v_or_b32_e32 v33, v96, v12
	v_lshlrev_b64 v[2:3], 11, v[2:3]
	v_lshlrev_b64 v[4:5], 11, v[4:5]
	v_or_b32_e32 v96, s84, v33
	v_lshlrev_b64 v[0:1], 11, v[0:1]
	v_lshl_add_u64 v[2:3], v[72:73], 0, v[2:3]
	v_lshl_add_u64 v[4:5], v[72:73], 0, v[4:5]
	v_lshl_add_u64 v[0:1], v[72:73], 0, v[0:1]
	v_lshl_add_u64 v[72:73], v[96:97], 1, s[64:65]
	global_load_dword v35, v250, s[60:61]
	s_mov_b32 s2, 0x5040100
	global_load_ushort v72, v251, s[64:65] offset:3072
	v_lshl_add_u64 v[98:99], v[96:97], 2, s[60:61]
	global_load_dword v33, v250, s[60:61] offset:2048
	flat_load_ushort v129, v[70:71]
	flat_load_ushort v130, v[66:67]
	flat_load_ushort v131, v[68:69]
	flat_load_ushort v132, v[62:63]
	flat_load_ushort v133, v[64:65]
	flat_load_ushort v134, v[58:59]
	flat_load_ushort v135, v[60:61]
	flat_load_ushort v136, v[54:55]
	flat_load_ushort v119, v[56:57]
	flat_load_ushort v116, v[50:51]
	flat_load_ushort v113, v[52:53]
	flat_load_ushort v109, v[6:7]
	flat_load_ushort v106, v[48:49]
	flat_load_ushort v103, v[2:3]
	flat_load_ushort v100, v[4:5]
	flat_load_ushort v98, v[0:1]
	s_waitcnt vmcnt(0) lgkmcnt(0)
	v_add_f32_e32 v73, 0, v95
	v_add_f32_e32 v128, v73, v93
	v_add_f32_e32 v121, v128, v92
	v_add_f32_e32 v118, v121, v91
	v_add_f32_e32 v114, v118, v89
	v_add_f32_e32 v111, v114, v88
	v_add_f32_e32 v105, v111, v86
	v_add_f32_e32 v102, v105, v85
	v_add_f32_e32 v99, v102, v83
	v_perm_b32 v125, v108, v107, s2
	v_perm_b32 v124, v104, v101, s2
	v_add_f32_e32 v97, v99, v47
	v_perm_b32 v123, v77, v76, s2
	v_perm_b32 v122, v75, v74, s2
	v_perm_b32 v74, v112, v110, s2
	v_mul_f32_e32 v47, 0x3fb8aa3b, v47
	s_ashr_i32 s45, s44, 31
	v_add_f32_e32 v96, v97, v45
	v_mul_f32_e32 v45, 0x3fb8aa3b, v45
	v_add_f32_e32 v94, v96, v41
	v_mul_f32_e32 v41, 0x3fb8aa3b, v41
	v_perm_b32 v75, v117, v115, s2
	v_add_f32_e32 v90, v94, v39
	v_add_f32_e32 v87, v90, v37
	v_perm_b32 v76, v126, v120, s2
	v_add_f32_e32 v84, v87, v35
	v_perm_b32 v77, v72, v127, s2
	v_add_f32_e32 v43, v84, v33
	ds_write_b32 v9, v43
	ds_write_b128 v13, v[122:125] offset:53248
	ds_write_b128 v13, v[74:77] offset:53264
	s_waitcnt lgkmcnt(0)
	s_barrier
; __device__ __forceinline__ float bf2f(unsigned short h) { return __uint_as_float(((unsigned)h) << 16); }
; __device__ __forceinline__ unsigned short f2bf(float f) { return (unsigned short)(cvt_pk_bf16(f, 0.f) & 0xffffu); }
; __device__ __forceinline__ void hgrn_pass1_unit(Frame& F, int unit) {
;     ...
;     const float t0 = tot[k], t1 = tot[128 + k], t2 = tot[256 + k], t3 = tot[384 + k];
;     const float off = (tq > 0 ? t0 : 0.f) + (tq > 1 ? t1 : 0.f) + (tq > 2 ? t2 : 0.f), gmid = t0 + t1, glast = gmid + t2 + t3;
;     float kl[16];
; #pragma unroll
;     for (int i = 0; i < 16; ++i) { const size_t r = row0 + 16 * tq + i; const float gi = off + g[i], q = bf2f(qv[i]), kk = 1.f - __expf(lf[i]);
;         QO[r * DM + h * 128 + k] = f2bf(q * __expf(gi));
;         Qm[(16 * tq + i) * HG_LDK + k] = f2bf(q * __expf(fminf(gi - gmid, 80.f)));
;         Km[(16 * tq + i) * HG_LDK + k] = f2bf(kk * __expf(fminf(gmid - gi, 80.f)));
;         kl[i] = kk * __expf(glast - gi); }
	ds_read2st64_b32 v[74:75], v15 offset1:2
	ds_read2st64_b32 v[122:123], v15 offset0:4 offset1:6
	s_waitcnt lgkmcnt(1)
	v_cndmask_b32_e64 v77, 0, v74, s[18:19]
	v_cndmask_b32_e64 v125, 0, v75, s[20:21]
	v_mov_b32_e32 v76, v74
	v_mov_b32_e32 v124, v75
	s_waitcnt lgkmcnt(0)
	v_cndmask_b32_e64 v127, 0, v122, s[22:23]
	v_pk_add_f32 v[74:75], v[76:77], v[124:125]
	v_mov_b32_e32 v126, v122
	v_pk_add_f32 v[76:77], v[74:75], v[126:127]
	v_mov_b32_e32 v72, v123
	v_pk_add_f32 v[72:73], v[76:77], v[72:73]
	v_mul_f32_e32 v76, 0x3fb8aa3b, v95
	v_exp_f32_e32 v122, v76
	v_mul_f32_e32 v76, 0x3fb8aa3b, v73
	v_exp_f32_e32 v76, v76
	v_lshlrev_b32_e32 v75, 16, v129
	v_mul_f32_e32 v76, v76, v75
	v_cvt_pk_bf16_f32 v76, v76, s0
	flat_store_short v[70:71], v76
	v_sub_f32_e32 v70, v73, v74
	v_min_f32_e32 v70, 0x42a00000, v70
	v_mul_f32_e32 v70, 0x3fb8aa3b, v70
	v_exp_f32_e32 v70, v70
	v_add_f32_e32 v71, v128, v77
	v_mul_f32_e32 v76, 0x3fb8aa3b, v93
	v_sub_f32_e32 v93, v71, v74
	v_mul_f32_e32 v70, v70, v75
	v_cvt_pk_bf16_f32 v70, v70, s0
	ds_write_b16 v23, v70
	v_sub_f32_e32 v70, v74, v73
	v_min_f32_e32 v70, 0x42a00000, v70
	v_mul_f32_e32 v70, 0x3fb8aa3b, v70
	v_exp_f32_e32 v123, v76
	v_mul_f32_e32 v76, 0x3fb8aa3b, v71
	v_min_f32_e32 v93, 0x42a00000, v93
	v_exp_f32_e32 v75, v70
	v_exp_f32_e32 v76, v76
	v_mul_f32_e32 v93, 0x3fb8aa3b, v93
	v_exp_f32_e32 v93, v93
	v_sub_f32_e32 v70, v72, v73
	v_lshlrev_b32_e32 v73, 16, v130
	v_pk_add_f32 v[122:123], v[122:123], 1.0 op_sel_hi:[1,0] neg_lo:[1,0] neg_hi:[1,0]
	v_mul_f32_e32 v76, v76, v73
	v_mul_f32_e32 v75, v122, v75
	v_cvt_pk_bf16_f32 v76, v76, s0
	v_mul_f32_e32 v73, v93, v73
	v_sub_f32_e32 v93, v74, v71
	v_cvt_pk_bf16_f32 v75, v75, s0
	v_min_f32_e32 v93, 0x42a00000, v93
	ds_write_b16 v23, v75 offset:17408
	flat_store_short v[66:67], v76
	v_add_f32_e32 v67, v121, v77
	v_mul_f32_e32 v93, 0x3fb8aa3b, v93
	v_mul_f32_e32 v75, 0x3fb8aa3b, v67
	v_exp_f32_e32 v93, v93
	v_exp_f32_e32 v75, v75
	v_cvt_pk_bf16_f32 v73, v73, s0
	ds_write_b16 v23, v73 offset:272
	v_lshlrev_b32_e32 v73, 16, v131
	v_mul_f32_e32 v66, v123, v93
	v_mul_f32_e32 v75, v75, v73
	v_cvt_pk_bf16_f32 v66, v66, s0
	v_cvt_pk_bf16_f32 v75, v75, s0
	ds_write_b16 v23, v66 offset:17680
	flat_store_short v[68:69], v75
	v_sub_f32_e32 v68, v67, v74
	v_min_f32_e32 v68, 0x42a00000, v68
	v_mul_f32_e32 v68, 0x3fb8aa3b, v68
	v_exp_f32_e32 v68, v68
	v_add_f32_e32 v69, v118, v77
	v_mul_f32_e32 v76, 0x3fb8aa3b, v69
	v_exp_f32_e32 v76, v76
	v_mul_f32_e32 v68, v68, v73
	v_cvt_pk_bf16_f32 v68, v68, s0
	ds_write_b16 v23, v68 offset:544
	v_sub_f32_e32 v68, v74, v67
	v_min_f32_e32 v68, 0x42a00000, v68
	v_sub_f32_e32 v67, v72, v67
	v_mul_f32_e32 v68, 0x3fb8aa3b, v68
	v_mul_f32_e32 v67, 0x3fb8aa3b, v67
	v_exp_f32_e32 v73, v68
	v_exp_f32_e32 v68, v67
	v_mul_f32_e32 v67, 0x3fb8aa3b, v91
	v_sub_f32_e32 v91, v69, v74
	v_min_f32_e32 v91, 0x42a00000, v91
	v_mul_f32_e32 v91, 0x3fb8aa3b, v91
	v_exp_f32_e32 v91, v91
	v_mul_f32_e32 v66, 0x3fb8aa3b, v92
	v_exp_f32_e32 v66, v66
	v_exp_f32_e32 v67, v67
	v_lshlrev_b32_e32 v75, 16, v132
	v_mul_f32_e32 v76, v76, v75
	v_mul_f32_e32 v75, v91, v75
	v_sub_f32_e32 v91, v74, v69
	v_sub_f32_e32 v69, v72, v69
	v_mul_f32_e32 v69, 0x3fb8aa3b, v69
	v_exp_f32_e32 v69, v69
	v_pk_add_f32 v[92:93], v[66:67], 1.0 op_sel_hi:[1,0] neg_lo:[1,0] neg_hi:[1,0]
	v_cvt_pk_bf16_f32 v76, v76, s0
	v_mul_f32_e32 v66, v92, v73
	v_cvt_pk_bf16_f32 v66, v66, s0
	v_min_f32_e32 v91, 0x42a00000, v91
	ds_write_b16 v23, v66 offset:17952
	flat_store_short v[62:63], v76
	v_add_f32_e32 v63, v114, v77
	v_mul_f32_e32 v91, 0x3fb8aa3b, v91
	v_pk_mul_f32 v[66:67], v[92:93], v[68:69]
	v_mul_f32_e32 v69, 0x3fb8aa3b, v63
	v_exp_f32_e32 v91, v91
	v_exp_f32_e32 v69, v69
	v_lshlrev_b32_e32 v68, 16, v133
	v_cvt_pk_bf16_f32 v75, v75, s0
	v_mul_f32_e32 v62, v93, v91
	v_mul_f32_e32 v69, v69, v68
	v_cvt_pk_bf16_f32 v62, v62, s0
	v_cvt_pk_bf16_f32 v69, v69, s0
	ds_write_b16 v23, v75 offset:816
	ds_write_b16 v23, v62 offset:18224
	flat_store_short v[64:65], v69
	v_sub_f32_e32 v64, v63, v74
	v_min_f32_e32 v64, 0x42a00000, v64
	v_mul_f32_e32 v64, 0x3fb8aa3b, v64
	v_add_f32_e32 v65, v111, v77
	v_exp_f32_e32 v64, v64
	v_mul_f32_e32 v69, 0x3fb8aa3b, v65
	v_exp_f32_e32 v69, v69
	v_mul_f32_e32 v62, 0x3fb8aa3b, v89
	v_mul_f32_e32 v64, v64, v68
	v_lshlrev_b32_e32 v68, 16, v134
	v_mul_f32_e32 v69, v69, v68
	v_cvt_pk_bf16_f32 v75, v69, s0
	v_sub_f32_e32 v69, v65, v74
	v_min_f32_e32 v69, 0x42a00000, v69
	v_cvt_pk_bf16_f32 v64, v64, s0
	v_mul_f32_e32 v69, 0x3fb8aa3b, v69
	ds_write_b16 v23, v64 offset:1088
	v_sub_f32_e32 v64, v74, v63
	v_exp_f32_e32 v69, v69
	v_min_f32_e32 v64, 0x42a00000, v64
	v_sub_f32_e32 v63, v72, v63
	v_mul_f32_e32 v64, 0x3fb8aa3b, v64
	v_mul_f32_e32 v63, 0x3fb8aa3b, v63
	v_exp_f32_e32 v73, v64
	v_exp_f32_e32 v64, v63
	v_mul_f32_e32 v63, 0x3fb8aa3b, v88
	v_exp_f32_e32 v62, v62
	v_exp_f32_e32 v63, v63
	v_mul_f32_e32 v68, v69, v68
	v_cvt_pk_bf16_f32 v76, v68, s0
	v_sub_f32_e32 v68, v74, v65
	v_min_f32_e32 v68, 0x42a00000, v68
	v_sub_f32_e32 v65, v72, v65
	v_mul_f32_e32 v68, 0x3fb8aa3b, v68
	v_mul_f32_e32 v65, 0x3fb8aa3b, v65
	v_exp_f32_e32 v88, v68
	v_exp_f32_e32 v65, v65
	v_pk_add_f32 v[68:69], v[62:63], 1.0 op_sel_hi:[1,0] neg_lo:[1,0] neg_hi:[1,0]
	v_sub_f32_e32 v71, v72, v71
	v_mul_f32_e32 v62, v68, v73
	v_cvt_pk_bf16_f32 v62, v62, s0
	ds_write_b16 v23, v62 offset:18496
	flat_store_short v[58:59], v75
	v_add_f32_e32 v59, v105, v77
	v_pk_mul_f32 v[62:63], v[68:69], v[64:65]
	v_mul_f32_e32 v65, 0x3fb8aa3b, v59
	v_exp_f32_e32 v65, v65
	v_lshlrev_b32_e32 v64, 16, v135
	v_mul_f32_e32 v58, v69, v88
	v_cvt_pk_bf16_f32 v58, v58, s0
	v_mul_f32_e32 v65, v65, v64
	v_cvt_pk_bf16_f32 v65, v65, s0
; __device__ __forceinline__ float bf2f(unsigned short h) { return __uint_as_float(((unsigned)h) << 16); }
; __device__ __forceinline__ unsigned short f2bf(float f) { return (unsigned short)(cvt_pk_bf16(f, 0.f) & 0xffffu); }
; __device__ __forceinline__ void hgrn_pass1_unit(Frame& F, int unit) {
;     ...
; #pragma unroll
;     for (int i = 0; i < 16; ++i) { const size_t r = row0 + 16 * tq + i; const float gi = off + g[i], q = bf2f(qv[i]), kk = 1.f - __expf(lf[i]);
;         QO[r * DM + h * 128 + k] = f2bf(q * __expf(gi));
;         Qm[(16 * tq + i) * HG_LDK + k] = f2bf(q * __expf(fminf(gi - gmid, 80.f)));
;         Km[(16 * tq + i) * HG_LDK + k] = f2bf(kk * __expf(fminf(gmid - gi, 80.f)));
;         kl[i] = kk * __expf(glast - gi); }
	ds_write_b16 v23, v76 offset:1360
	ds_write_b16 v23, v58 offset:18768
	flat_store_short v[60:61], v65
	v_sub_f32_e32 v60, v59, v74
	v_min_f32_e32 v60, 0x42a00000, v60
	v_mul_f32_e32 v60, 0x3fb8aa3b, v60
	v_add_f32_e32 v61, v102, v77
	v_exp_f32_e32 v60, v60
	v_mul_f32_e32 v65, 0x3fb8aa3b, v61
	v_exp_f32_e32 v65, v65
	v_mul_f32_e32 v58, 0x3fb8aa3b, v86
	v_mul_f32_e32 v60, v60, v64
	v_lshlrev_b32_e32 v64, 16, v136
	v_mul_f32_e32 v65, v65, v64
	v_cvt_pk_bf16_f32 v69, v65, s0
	v_sub_f32_e32 v65, v61, v74
	v_min_f32_e32 v65, 0x42a00000, v65
	v_cvt_pk_bf16_f32 v60, v60, s0
	v_mul_f32_e32 v65, 0x3fb8aa3b, v65
	ds_write_b16 v23, v60 offset:1632
	v_sub_f32_e32 v60, v74, v59
	v_exp_f32_e32 v65, v65
	v_min_f32_e32 v60, 0x42a00000, v60
	v_sub_f32_e32 v59, v72, v59
	v_mul_f32_e32 v60, 0x3fb8aa3b, v60
	v_mul_f32_e32 v59, 0x3fb8aa3b, v59
	v_exp_f32_e32 v68, v60
	v_exp_f32_e32 v60, v59
	v_mul_f32_e32 v59, 0x3fb8aa3b, v85
	v_exp_f32_e32 v58, v58
	v_exp_f32_e32 v59, v59
	v_mul_f32_e32 v64, v65, v64
	v_cvt_pk_bf16_f32 v73, v64, s0
	v_sub_f32_e32 v64, v74, v61
	v_min_f32_e32 v64, 0x42a00000, v64
	v_sub_f32_e32 v61, v72, v61
	v_mul_f32_e32 v64, 0x3fb8aa3b, v64
	v_mul_f32_e32 v61, 0x3fb8aa3b, v61
	v_exp_f32_e32 v75, v64
	v_exp_f32_e32 v61, v61
	v_pk_add_f32 v[64:65], v[58:59], 1.0 op_sel_hi:[1,0] neg_lo:[1,0] neg_hi:[1,0]
	v_mul_f32_e32 v70, 0x3fb8aa3b, v70
	v_mul_f32_e32 v58, v64, v68
	v_cvt_pk_bf16_f32 v58, v58, s0
	ds_write_b16 v23, v58 offset:19040
	flat_store_short v[54:55], v69
	v_add_f32_e32 v55, v99, v77
	v_pk_mul_f32 v[58:59], v[64:65], v[60:61]
	v_mul_f32_e32 v61, 0x3fb8aa3b, v55
	v_exp_f32_e32 v61, v61
	v_lshlrev_b32_e32 v60, 16, v119
	v_mul_f32_e32 v54, v65, v75
	v_cvt_pk_bf16_f32 v54, v54, s0
	v_mul_f32_e32 v61, v61, v60
	v_cvt_pk_bf16_f32 v61, v61, s0
	ds_write_b16 v23, v73 offset:1904
	ds_write_b16 v23, v54 offset:19312
	flat_store_short v[56:57], v61
	v_sub_f32_e32 v56, v55, v74
	v_min_f32_e32 v56, 0x42a00000, v56
	v_mul_f32_e32 v56, 0x3fb8aa3b, v56
	v_exp_f32_e32 v56, v56
	v_add_f32_e32 v57, v97, v77
	v_sub_f32_e32 v61, v57, v74
	v_min_f32_e32 v61, 0x42a00000, v61
	v_mul_f32_e32 v56, v56, v60
	v_cvt_pk_bf16_f32 v56, v56, s0
	ds_write_b16 v23, v56 offset:2176
	v_sub_f32_e32 v56, v74, v55
	v_min_f32_e32 v56, 0x42a00000, v56
	v_sub_f32_e32 v55, v72, v55
	v_mul_f32_e32 v56, 0x3fb8aa3b, v56
	v_mul_f32_e32 v55, 0x3fb8aa3b, v55
	v_exp_f32_e32 v64, v56
	v_exp_f32_e32 v56, v55
	v_exp_f32_e32 v55, v47
	v_mul_f32_e32 v47, 0x3fb8aa3b, v57
	v_mul_f32_e32 v61, 0x3fb8aa3b, v61
	v_exp_f32_e32 v47, v47
	v_exp_f32_e32 v61, v61
	v_lshlrev_b32_e32 v60, 16, v116
	v_mul_f32_e32 v54, 0x3fb8aa3b, v83
	v_mul_f32_e32 v47, v47, v60
	v_mul_f32_e32 v60, v61, v60
	v_exp_f32_e32 v54, v54
	v_cvt_pk_bf16_f32 v65, v60, s0
	v_sub_f32_e32 v60, v74, v57
	v_min_f32_e32 v60, 0x42a00000, v60
	v_mul_f32_e32 v60, 0x3fb8aa3b, v60
	v_exp_f32_e32 v68, v60
	v_pk_add_f32 v[60:61], v[54:55], 1.0 op_sel_hi:[1,0] neg_lo:[1,0] neg_hi:[1,0]
	v_cvt_pk_bf16_f32 v47, v47, s0
	v_mul_f32_e32 v54, v60, v64
	v_cvt_pk_bf16_f32 v54, v54, s0
	ds_write_b16 v23, v54 offset:19584
	flat_store_short v[50:51], v47
	v_mul_f32_e32 v47, v61, v68
	v_cvt_pk_bf16_f32 v47, v47, s0
	ds_write_b16 v23, v47 offset:19856
	v_add_f32_e32 v47, v96, v77
	v_exp_f32_e32 v50, v45
	v_mul_f32_e32 v45, 0x3fb8aa3b, v47
	v_exp_f32_e32 v45, v45
	v_lshlrev_b32_e32 v51, 16, v113
	ds_write_b16 v23, v65 offset:2448
	v_sub_f32_e32 v57, v72, v57
	v_mul_f32_e32 v45, v45, v51
	v_cvt_pk_bf16_f32 v45, v45, s0
	flat_store_short v[52:53], v45
	v_sub_f32_e32 v45, v47, v74
	v_min_f32_e32 v45, 0x42a00000, v45
	v_mul_f32_e32 v45, 0x3fb8aa3b, v45
	v_exp_f32_e32 v45, v45
	v_mul_f32_e32 v57, 0x3fb8aa3b, v57
	v_exp_f32_e32 v57, v57
	v_lshlrev_b32_e32 v53, 16, v109
	v_mul_f32_e32 v45, v45, v51
	v_cvt_pk_bf16_f32 v45, v45, s0
	ds_write_b16 v23, v45 offset:2720
	v_sub_f32_e32 v45, v74, v47
	v_sub_f32_e32 v47, v72, v47
	v_mul_f32_e32 v47, 0x3fb8aa3b, v47
	v_exp_f32_e32 v52, v47
	v_add_f32_e32 v47, v94, v77
	v_pk_mul_f32 v[54:55], v[60:61], v[56:57]
	v_sub_f32_e32 v56, v47, v74
	v_min_f32_e32 v56, 0x42a00000, v56
	v_exp_f32_e32 v51, v41
	v_mul_f32_e32 v41, 0x3fb8aa3b, v47
	v_mul_f32_e32 v56, 0x3fb8aa3b, v56
	v_exp_f32_e32 v41, v41
	v_exp_f32_e32 v56, v56
	v_min_f32_e32 v45, 0x42a00000, v45
	v_mul_f32_e32 v45, 0x3fb8aa3b, v45
	v_mul_f32_e32 v41, v41, v53
	v_mul_f32_e32 v53, v56, v53
	v_cvt_pk_bf16_f32 v56, v53, s0
	v_sub_f32_e32 v53, v74, v47
	v_exp_f32_e32 v45, v45
	v_min_f32_e32 v53, 0x42a00000, v53
	v_mul_f32_e32 v53, 0x3fb8aa3b, v53
	v_exp_f32_e32 v57, v53
; __device__ __forceinline__ unsigned cvt_pk_bf16(float lo, float hi) { const f32x2cv v = {lo, hi}; const bf16x2cv b = __builtin_convertvector(v, bf16x2cv); return __builtin_bit_cast(unsigned, b); }
; #define LAS __attribute__((address_space(3)))
; __device__ __forceinline__ float bf2f(unsigned short h) { return __uint_as_float(((unsigned)h) << 16); }
; __device__ __forceinline__ unsigned short f2bf(float f) { return (unsigned short)(cvt_pk_bf16(f, 0.f) & 0xffffu); }
; __device__ __forceinline__ void hgrn_pass1_unit(Frame& F, int unit) {
;     ...
; #pragma unroll
;     for (int i = 0; i < 16; ++i) { const size_t r = row0 + 16 * tq + i; const float gi = off + g[i], q = bf2f(qv[i]), kk = 1.f - __expf(lf[i]);
;         QO[r * DM + h * 128 + k] = f2bf(q * __expf(gi));
;         Qm[(16 * tq + i) * HG_LDK + k] = f2bf(q * __expf(fminf(gi - gmid, 80.f)));
;         Km[(16 * tq + i) * HG_LDK + k] = f2bf(kk * __expf(fminf(gmid - gi, 80.f)));
;         kl[i] = kk * __expf(glast - gi); }
;     { v4u w0, w1; w0.x = cvt_pk_bf16(kl[0], kl[1]); w0.y = cvt_pk_bf16(kl[2], kl[3]); w0.z = cvt_pk_bf16(kl[4], kl[5]); w0.w = cvt_pk_bf16(kl[6], kl[7]); w1.x = cvt_pk_bf16(kl[8], kl[9]); w1.y = cvt_pk_bf16(kl[10], kl[11]); w1.z = cvt_pk_bf16(kl[12], kl[13]); w1.w = cvt_pk_bf16(kl[14], kl[15]);
;       *(LAS v4u*)(KlT + k * HG_LDS + 16 * tq) = w0; *(LAS v4u*)(KlT + k * HG_LDS + 16 * tq + 8) = w1; }
;     if (tq == 0) HD[k] = __expf(glast);
	v_pk_add_f32 v[50:51], v[50:51], 1.0 op_sel_hi:[1,0] neg_lo:[1,0] neg_hi:[1,0]
	v_cvt_pk_bf16_f32 v41, v41, s0
	v_mul_f32_e32 v45, v50, v45
	v_cvt_pk_bf16_f32 v45, v45, s0
	ds_write_b16 v23, v45 offset:20128
	flat_store_short v[6:7], v41
	v_mul_f32_e32 v6, v51, v57
	v_cvt_pk_bf16_f32 v6, v6, s0
	v_add_f32_e32 v7, v90, v77
	ds_write_b16 v23, v6 offset:20400
	v_mul_f32_e32 v6, 0x3fb8aa3b, v39
	v_mul_f32_e32 v39, 0x3fb8aa3b, v7
	v_exp_f32_e32 v39, v39
	v_lshlrev_b32_e32 v41, 16, v106
	ds_write_b16 v23, v56 offset:2992
	v_sub_f32_e32 v47, v72, v47
	v_mul_f32_e32 v39, v39, v41
	v_cvt_pk_bf16_f32 v39, v39, s0
	flat_store_short v[48:49], v39
	v_sub_f32_e32 v39, v7, v74
	v_min_f32_e32 v39, 0x42a00000, v39
	v_mul_f32_e32 v39, 0x3fb8aa3b, v39
	v_exp_f32_e32 v39, v39
	v_mul_f32_e32 v47, 0x3fb8aa3b, v47
	v_exp_f32_e32 v53, v47
	v_exp_f32_e32 v6, v6
	v_mul_f32_e32 v39, v39, v41
	v_cvt_pk_bf16_f32 v39, v39, s0
	v_add_f32_e32 v41, v87, v77
	ds_write_b16 v23, v39 offset:3264
	v_sub_f32_e32 v39, v74, v7
	v_sub_f32_e32 v7, v72, v7
	v_sub_f32_e32 v47, v41, v74
	v_mul_f32_e32 v7, 0x3fb8aa3b, v7
	v_min_f32_e32 v47, 0x42a00000, v47
	v_exp_f32_e32 v48, v7
	v_mul_f32_e32 v7, 0x3fb8aa3b, v37
	v_mul_f32_e32 v37, 0x3fb8aa3b, v41
	v_mul_f32_e32 v47, 0x3fb8aa3b, v47
	v_exp_f32_e32 v37, v37
	v_exp_f32_e32 v47, v47
	v_min_f32_e32 v39, 0x42a00000, v39
	v_mul_f32_e32 v39, 0x3fb8aa3b, v39
	v_lshlrev_b32_e32 v45, 16, v103
	v_exp_f32_e32 v7, v7
	v_exp_f32_e32 v39, v39
	v_mul_f32_e32 v37, v37, v45
	v_mul_f32_e32 v45, v47, v45
	v_sub_f32_e32 v47, v74, v41
	v_min_f32_e32 v47, 0x42a00000, v47
	v_sub_f32_e32 v41, v72, v41
	v_mul_f32_e32 v47, 0x3fb8aa3b, v47
	v_mul_f32_e32 v41, 0x3fb8aa3b, v41
	v_exp_f32_e32 v47, v47
	v_exp_f32_e32 v49, v41
	v_pk_add_f32 v[6:7], v[6:7], 1.0 op_sel_hi:[1,0] neg_lo:[1,0] neg_hi:[1,0]
	v_cvt_pk_bf16_f32 v37, v37, s0
	v_mul_f32_e32 v39, v6, v39
	v_cvt_pk_bf16_f32 v39, v39, s0
	ds_write_b16 v23, v39 offset:20672
	flat_store_short v[2:3], v37
	v_add_f32_e32 v3, v84, v77
	v_pk_mul_f32 v[48:49], v[6:7], v[48:49]
	v_mul_f32_e32 v2, v7, v47
	v_mul_f32_e32 v7, 0x3fb8aa3b, v3
	v_exp_f32_e32 v7, v7
	v_lshlrev_b32_e32 v6, 16, v100
	v_cvt_pk_bf16_f32 v45, v45, s0
	v_cvt_pk_bf16_f32 v2, v2, s0
	v_mul_f32_e32 v7, v7, v6
	v_cvt_pk_bf16_f32 v7, v7, s0
	ds_write_b16 v23, v45 offset:3536
	ds_write_b16 v23, v2 offset:20944
	flat_store_short v[4:5], v7
	v_sub_f32_e32 v4, v3, v74
	v_min_f32_e32 v4, 0x42a00000, v4
	v_mul_f32_e32 v4, 0x3fb8aa3b, v4
	v_exp_f32_e32 v4, v4
	v_add_f32_e32 v5, v43, v77
	v_mul_f32_e32 v2, 0x3fb8aa3b, v35
	v_sub_f32_e32 v35, v5, v74
	v_mul_f32_e32 v4, v4, v6
	v_cvt_pk_bf16_f32 v4, v4, s0
	ds_write_b16 v23, v4 offset:3808
	v_sub_f32_e32 v4, v74, v3
	v_min_f32_e32 v4, 0x42a00000, v4
	v_sub_f32_e32 v3, v72, v3
	v_mul_f32_e32 v4, 0x3fb8aa3b, v4
	v_mul_f32_e32 v3, 0x3fb8aa3b, v3
	v_min_f32_e32 v35, 0x42a00000, v35
	v_exp_f32_e32 v6, v4
	v_exp_f32_e32 v4, v3
	v_mul_f32_e32 v3, 0x3fb8aa3b, v33
	v_mul_f32_e32 v33, 0x3fb8aa3b, v5
	v_mul_f32_e32 v35, 0x3fb8aa3b, v35
	v_exp_f32_e32 v33, v33
	v_exp_f32_e32 v35, v35
	v_lshlrev_b32_e32 v7, 16, v98
	v_exp_f32_e32 v2, v2
	v_exp_f32_e32 v3, v3
	v_mul_f32_e32 v33, v33, v7
	v_mul_f32_e32 v7, v35, v7
	v_sub_f32_e32 v35, v74, v5
	v_min_f32_e32 v35, 0x42a00000, v35
	v_mul_f32_e32 v35, 0x3fb8aa3b, v35
	v_mul_f32_e32 v71, 0x3fb8aa3b, v71
	v_exp_f32_e32 v35, v35
	v_sub_f32_e32 v5, v72, v5
	v_exp_f32_e32 v70, v70
	v_exp_f32_e32 v71, v71
	v_mul_f32_e32 v5, 0x3fb8aa3b, v5
	v_pk_add_f32 v[2:3], v[2:3], 1.0 op_sel_hi:[1,0] neg_lo:[1,0] neg_hi:[1,0]
	v_exp_f32_e32 v5, v5
	v_mul_f32_e32 v6, v2, v6
	v_cvt_pk_bf16_f32 v33, v33, s0
	v_cvt_pk_bf16_f32 v6, v6, s0
	ds_write_b16 v23, v6 offset:21216
	flat_store_short v[0:1], v33
	v_mul_f32_e32 v0, v3, v35
	v_pk_mul_f32 v[70:71], v[122:123], v[70:71]
	v_cvt_pk_bf16_f32 v0, v0, s0
	v_pk_mul_f32 v[52:53], v[50:51], v[52:53]
	v_cvt_pk_bf16_f32 v7, v7, s0
	v_pk_mul_f32 v[50:51], v[2:3], v[4:5]
	ds_write_b16 v23, v0 offset:21488
	v_cvt_pk_bf16_f32 v0, v70, v71
	v_cvt_pk_bf16_f32 v1, v66, v67
	v_cvt_pk_bf16_f32 v2, v62, v63
	v_cvt_pk_bf16_f32 v3, v58, v59
	ds_write_b16 v23, v7 offset:4080
	v_cvt_pk_bf16_f32 v4, v54, v55
	v_cvt_pk_bf16_f32 v5, v52, v53
	v_cvt_pk_bf16_f32 v6, v48, v49
	v_cvt_pk_bf16_f32 v7, v50, v51
	ds_write_b128 v13, v[0:3] offset:34816
	ds_write_b128 v13, v[4:7] offset:34832
	s_and_saveexec_b64 s[84:85], s[24:25]
	s_cbranch_execz .LBB0_528
	v_mul_f32_e32 v0, 0x3fb8aa3b, v72
	v_exp_f32_e32 v2, v0
	s_lshl_b64 s[92:93], s[44:45], 9
	v_lshl_add_u64 v[0:1], v[20:21], 0, s[92:93]
	flat_store_dword v[0:1], v2
